# v41 + EpiIn sigmoid-gate path: -log2e folded into the row-scale multiplier, 255/(1+e) as rcp(fma(e,1/255,1/255)) (3 plain VALU fewer per gate element)
# baseline (speedup 1.0000x reference)
; __device__ __forceinline__ float rstd_of(float ssq) { return __builtin_amdgcn_rsqf(ssq * (1.0f / 1024.0f) + 1e-6f); }
; #define PG8_BAR __builtin_amdgcn_s_barrier()
;     __device__ __forceinline__ void operator()(f32x4 (&acc)[2][2][4][2], const Unit& u, int wr, int wc, int fr, int fq) const {
;         const int row0 = u.pm * BM + wr * 64 + fr, col0 = u.pn * BM + wc * 32 + 8 * fq;
;         const bool sig = u.pn >= 7; const float sc = u.pn < 4 ? qscale : 1.f;
;         float sq[2][4];
; #pragma unroll
;         for (int ai = 0; ai < 2; ++ai)
; #pragma unroll
;             for (int m = 0; m < 4; ++m) sq[ai][m] = ssq[row0 + ai * HALF + m * 16];
; #pragma unroll
;         for (int ai = 0; ai < 2; ++ai)
; #pragma unroll
;             for (int m = 0; m < 4; ++m) { const int row = row0 + ai * HALF + m * 16; const float rs = rstd_of(sq[ai][m]) * sc;
; template <class Epi, class Sched, bool ALIGN_EPI = false, bool SP2 = false>
; __device__ __forceinline__ void gemm_phase(PG8_LAS unsigned char* lds, const Gemm g, const Sched& S, const Epi& E) {
;     ...
;         if constexpr (ALIGN_EPI) { if (wr == 0) PG8_BAR; }
.LBB0_318:
	v_lshl_add_u32 v140, s72, 8, v157
	v_ashrrev_i32_e32 v141, 31, v140
	v_lshl_add_u64 v[2:3], v[140:141], 2, s[10:11]
	v_or_b32_e32 v148, 16, v140
	global_load_dword v1, v[2:3], off
	v_ashrrev_i32_e32 v149, 31, v148
	v_or_b32_e32 v146, 32, v140
	v_or_b32_e32 v144, 48, v140
	v_lshl_add_u64 v[142:143], v[148:149], 2, s[10:11]
	v_ashrrev_i32_e32 v147, 31, v146
	v_ashrrev_i32_e32 v145, 31, v144
	v_lshl_add_u64 v[150:151], v[146:147], 2, s[10:11]
	v_lshl_add_u64 v[152:153], v[144:145], 2, s[10:11]
	global_load_dword v169, v[142:143], off
	global_load_dword v168, v[150:151], off
	global_load_dword v167, v[152:153], off
	global_load_dword v166, v[2:3], off offset:512
	global_load_dword v149, v[2:3], off offset:576
	global_load_dword v147, v[2:3], off offset:640
	global_load_dword v141, v[2:3], off offset:704
	s_cmp_gt_i32 s6, 6
	s_cselect_b64 s[74:75], -1, 0
	s_cmp_lt_i32 s6, 7
	s_cselect_b64 s[76:77], -1, 0
	s_cmp_lt_i32 s6, 4
	s_cselect_b64 vcc, -1, 0
	v_lshl_or_b32 v142, s6, 8, v158
	v_mad_i64_i32 v[2:3], s[8:9], v140, s81, 0
	v_cndmask_b32_e32 v145, 1.0, v165, vcc
	v_mov_b32_e32 v248, 0xbfb8aa3b
	v_mov_b32_e32 v247, 0x3b808081
	v_cndmask_b32_e64 v145, v145, v248, s[74:75]
	v_ashrrev_i32_e32 v143, 31, v142
	v_lshl_add_u64 v[2:3], s[28:29], 0, v[2:3]
	s_mov_b64 s[4:5], -1
	s_and_b64 vcc, exec, s[76:77]
	v_lshl_add_u64 v[150:151], v[142:143], 1, v[2:3]
	v_readlane_b32 s99, v246, 6
	s_nop 1
	s_cmp_lt_u32 s99, 4
	s_cbranch_scc0 .Lnoal_2
	s_barrier

; __device__ __forceinline__ float sigmoid_f(float v) { return __builtin_amdgcn_rcpf(1.0f + __builtin_amdgcn_exp2f(-v * LOG2E)); }
;     __device__ __forceinline__ void operator()(f32x4 (&acc)[2][2][4][2], const Unit& u, int wr, int wc, int fr, int fq) const {
;     ...
;                     if (sig) {
; #pragma unroll
;                         for (int e = 0; e < 4; ++e) { v0[e] = sigmoid_f(v0[e]); v1[e] = sigmoid_f(v1[e]); }
;                         unsigned lo = 0u, hi = 0u;
;                         lo = __builtin_amdgcn_cvt_pk_u8_f32(__builtin_rintf(v0[0] * 255.0f), 0, lo); lo = __builtin_amdgcn_cvt_pk_u8_f32(__builtin_rintf(v0[1] * 255.0f), 1, lo);
;                         lo = __builtin_amdgcn_cvt_pk_u8_f32(__builtin_rintf(v0[2] * 255.0f), 2, lo); lo = __builtin_amdgcn_cvt_pk_u8_f32(__builtin_rintf(v0[3] * 255.0f), 3, lo);
;                         hi = __builtin_amdgcn_cvt_pk_u8_f32(__builtin_rintf(v1[0] * 255.0f), 0, hi); hi = __builtin_amdgcn_cvt_pk_u8_f32(__builtin_rintf(v1[1] * 255.0f), 1, hi);
;                         hi = __builtin_amdgcn_cvt_pk_u8_f32(__builtin_rintf(v1[2] * 255.0f), 2, hi); hi = __builtin_amdgcn_cvt_pk_u8_f32(__builtin_rintf(v1[3] * 255.0f), 3, hi);
;                         if (bj == 0) { g8.x = lo; g8.y = hi; } else { g8.z = lo; g8.w = hi; } }
.LBB0_320:
	s_andn2_b64 vcc, exec, s[4:5]
	s_cbranch_vccnz .LBB0_322
	v_exp_f32_e32 v124, v124
	v_exp_f32_e32 v126, v129
	v_exp_f32_e32 v1, v128
	v_fmaak_f32 v124, v124, v247, 0x3b808081
	v_rcp_f32_e32 v127, v124
	v_fmaak_f32 v124, v126, v247, 0x3b808081
	v_exp_f32_e32 v126, v130
	v_fmaak_f32 v1, v1, v247, 0x3b808081
	v_rcp_f32_e32 v1, v1
	v_exp_f32_e32 v128, v131
	v_rcp_f32_e32 v124, v124
	v_fmaak_f32 v126, v126, v247, 0x3b808081
	v_exp_f32_e32 v125, v125
	v_rcp_f32_e32 v126, v126
	v_exp_f32_e32 v2, v2
	v_fmaak_f32 v128, v128, v247, 0x3b808081
	v_rcp_f32_e32 v128, v128
	v_rndne_f32_e32 v1, v1
	v_exp_f32_e32 v3, v3
	v_cvt_pk_u8_f32 v1, v1, 0, 0
	v_rndne_f32_e32 v124, v124
	v_fmaak_f32 v125, v125, v247, 0x3b808081
	v_cvt_pk_u8_f32 v1, v124, 1, v1
	v_rcp_f32_e32 v125, v125
	v_fmaak_f32 v2, v2, v247, 0x3b808081
	v_rndne_f32_e32 v124, v126
	v_rcp_f32_e32 v2, v2
	v_cvt_pk_u8_f32 v1, v124, 2, v1
	v_fmaak_f32 v3, v3, v247, 0x3b808081
	v_rndne_f32_e32 v124, v128
	v_rcp_f32_e32 v3, v3
	v_cvt_pk_u8_f32 v124, v124, 3, v1
	v_rndne_f32_e32 v1, v127
	v_cvt_pk_u8_f32 v1, v1, 0, 0
	v_rndne_f32_e32 v125, v125
	v_cvt_pk_u8_f32 v1, v125, 1, v1
	v_rndne_f32_e32 v2, v2
	v_cvt_pk_u8_f32 v1, v2, 2, v1
	v_rndne_f32_e32 v2, v3
	v_cvt_pk_u8_f32 v125, v2, 3, v1
	v_mov_b32_e32 v126, v0
	v_mov_b32_e32 v127, v0
	s_branch .LBB0_323

; __device__ __forceinline__ float sigmoid_f(float v) { return __builtin_amdgcn_rcpf(1.0f + __builtin_amdgcn_exp2f(-v * LOG2E)); }
;     __device__ __forceinline__ void operator()(f32x4 (&acc)[2][2][4][2], const Unit& u, int wr, int wc, int fr, int fq) const {
;     ...
;                     if (sig) {
; #pragma unroll
;                         for (int e = 0; e < 4; ++e) { v0[e] = sigmoid_f(v0[e]); v1[e] = sigmoid_f(v1[e]); }
;                         unsigned lo = 0u, hi = 0u;
;                         lo = __builtin_amdgcn_cvt_pk_u8_f32(__builtin_rintf(v0[0] * 255.0f), 0, lo); lo = __builtin_amdgcn_cvt_pk_u8_f32(__builtin_rintf(v0[1] * 255.0f), 1, lo);
;                         lo = __builtin_amdgcn_cvt_pk_u8_f32(__builtin_rintf(v0[2] * 255.0f), 2, lo); lo = __builtin_amdgcn_cvt_pk_u8_f32(__builtin_rintf(v0[3] * 255.0f), 3, lo);
;                         hi = __builtin_amdgcn_cvt_pk_u8_f32(__builtin_rintf(v1[0] * 255.0f), 0, hi); hi = __builtin_amdgcn_cvt_pk_u8_f32(__builtin_rintf(v1[1] * 255.0f), 1, hi);
;                         hi = __builtin_amdgcn_cvt_pk_u8_f32(__builtin_rintf(v1[2] * 255.0f), 2, hi); hi = __builtin_amdgcn_cvt_pk_u8_f32(__builtin_rintf(v1[3] * 255.0f), 3, hi);
;                         if (bj == 0) { g8.x = lo; g8.y = hi; } else { g8.z = lo; g8.w = hi; } }
.LBB0_325:
	s_andn2_b64 vcc, exec, s[76:77]
	s_cbranch_vccnz .LBB0_327
	v_exp_f32_e32 v1, v120
	v_exp_f32_e32 v120, v121
	v_exp_f32_e32 v2, v2
	v_fmaak_f32 v1, v1, v247, 0x3b808081
	v_exp_f32_e32 v3, v3
	v_rcp_f32_e32 v1, v1
	v_fmaak_f32 v120, v120, v247, 0x3b808081
	v_exp_f32_e32 v116, v116
	v_rcp_f32_e32 v120, v120
	v_fmaak_f32 v2, v2, v247, 0x3b808081
	v_exp_f32_e32 v117, v117
	v_rcp_f32_e32 v2, v2
	v_fmaak_f32 v3, v3, v247, 0x3b808081
	v_exp_f32_e32 v118, v118
	v_rcp_f32_e32 v3, v3
	v_fmaak_f32 v116, v116, v247, 0x3b808081
	v_rndne_f32_e32 v1, v1
	v_rcp_f32_e32 v116, v116
	v_fmaak_f32 v117, v117, v247, 0x3b808081
	v_exp_f32_e32 v119, v119
	v_cvt_pk_u8_f32 v1, v1, 0, 0
	v_rndne_f32_e32 v120, v120
	v_rcp_f32_e32 v117, v117
	v_cvt_pk_u8_f32 v1, v120, 1, v1
	v_rndne_f32_e32 v2, v2
	v_fmaak_f32 v118, v118, v247, 0x3b808081
	v_cvt_pk_u8_f32 v1, v2, 2, v1
	v_rcp_f32_e32 v118, v118
	v_rndne_f32_e32 v2, v3
	v_fmaak_f32 v119, v119, v247, 0x3b808081
	v_cvt_pk_u8_f32 v126, v2, 3, v1
	v_rcp_f32_e32 v119, v119
	v_rndne_f32_e32 v1, v116
	v_cvt_pk_u8_f32 v1, v1, 0, 0
	v_rndne_f32_e32 v2, v117
	v_cvt_pk_u8_f32 v1, v2, 1, v1
	v_rndne_f32_e32 v2, v118
	v_cvt_pk_u8_f32 v1, v2, 2, v1
	v_rndne_f32_e32 v2, v119
	v_cvt_pk_u8_f32 v127, v2, 3, v1

; __device__ __forceinline__ float sigmoid_f(float v) { return __builtin_amdgcn_rcpf(1.0f + __builtin_amdgcn_exp2f(-v * LOG2E)); }
;     __device__ __forceinline__ void operator()(f32x4 (&acc)[2][2][4][2], const Unit& u, int wr, int wc, int fr, int fq) const {
;     ...
;                     if (sig) {
; #pragma unroll
;                         for (int e = 0; e < 4; ++e) { v0[e] = sigmoid_f(v0[e]); v1[e] = sigmoid_f(v1[e]); }
;                         unsigned lo = 0u, hi = 0u;
;                         lo = __builtin_amdgcn_cvt_pk_u8_f32(__builtin_rintf(v0[0] * 255.0f), 0, lo); lo = __builtin_amdgcn_cvt_pk_u8_f32(__builtin_rintf(v0[1] * 255.0f), 1, lo);
;                         lo = __builtin_amdgcn_cvt_pk_u8_f32(__builtin_rintf(v0[2] * 255.0f), 2, lo); lo = __builtin_amdgcn_cvt_pk_u8_f32(__builtin_rintf(v0[3] * 255.0f), 3, lo);
;                         hi = __builtin_amdgcn_cvt_pk_u8_f32(__builtin_rintf(v1[0] * 255.0f), 0, hi); hi = __builtin_amdgcn_cvt_pk_u8_f32(__builtin_rintf(v1[1] * 255.0f), 1, hi);
;                         hi = __builtin_amdgcn_cvt_pk_u8_f32(__builtin_rintf(v1[2] * 255.0f), 2, hi); hi = __builtin_amdgcn_cvt_pk_u8_f32(__builtin_rintf(v1[3] * 255.0f), 3, hi);
;                         if (bj == 0) { g8.x = lo; g8.y = hi; } else { g8.z = lo; g8.w = hi; } }
.LBB0_331:
	s_andn2_b64 vcc, exec, s[74:75]
	s_cbranch_vccnz .LBB0_333
	v_exp_f32_e32 v1, v114
	v_exp_f32_e32 v108, v108
	v_exp_f32_e32 v114, v115
	v_exp_f32_e32 v2, v2
	v_fmaak_f32 v1, v1, v247, 0x3b808081
	v_fmaak_f32 v108, v108, v247, 0x3b808081
	v_exp_f32_e32 v3, v3
	v_rcp_f32_e32 v1, v1
	v_rcp_f32_e32 v115, v108
	v_fmaak_f32 v108, v114, v247, 0x3b808081
	v_rcp_f32_e32 v108, v108
	v_fmaak_f32 v2, v2, v247, 0x3b808081
	v_exp_f32_e32 v109, v109
	v_rcp_f32_e32 v2, v2
	v_fmaak_f32 v3, v3, v247, 0x3b808081
	v_exp_f32_e32 v110, v110
	v_rcp_f32_e32 v3, v3
	v_rndne_f32_e32 v1, v1
	v_fmaak_f32 v109, v109, v247, 0x3b808081
	v_exp_f32_e32 v111, v111
	v_cvt_pk_u8_f32 v1, v1, 0, 0
	v_rndne_f32_e32 v108, v108
	v_rcp_f32_e32 v109, v109
	v_cvt_pk_u8_f32 v1, v108, 1, v1
	v_rndne_f32_e32 v2, v2
	v_fmaak_f32 v110, v110, v247, 0x3b808081
	v_cvt_pk_u8_f32 v1, v2, 2, v1
	v_rcp_f32_e32 v110, v110
	v_rndne_f32_e32 v2, v3
	v_fmaak_f32 v111, v111, v247, 0x3b808081
	v_cvt_pk_u8_f32 v108, v2, 3, v1
	v_rcp_f32_e32 v111, v111
	v_rndne_f32_e32 v1, v115
	v_cvt_pk_u8_f32 v1, v1, 0, 0
	v_rndne_f32_e32 v2, v109
	v_cvt_pk_u8_f32 v1, v2, 1, v1
	v_rndne_f32_e32 v2, v110
	v_cvt_pk_u8_f32 v1, v2, 2, v1
	v_rndne_f32_e32 v2, v111
	v_cvt_pk_u8_f32 v109, v2, 3, v1
	v_mov_b32_e32 v110, v0
	v_mov_b32_e32 v111, v0
	s_branch .LBB0_334

; __device__ __forceinline__ float sigmoid_f(float v) { return __builtin_amdgcn_rcpf(1.0f + __builtin_amdgcn_exp2f(-v * LOG2E)); }
;     __device__ __forceinline__ void operator()(f32x4 (&acc)[2][2][4][2], const Unit& u, int wr, int wc, int fr, int fq) const {
;     ...
;                     if (sig) {
; #pragma unroll
;                         for (int e = 0; e < 4; ++e) { v0[e] = sigmoid_f(v0[e]); v1[e] = sigmoid_f(v1[e]); }
;                         unsigned lo = 0u, hi = 0u;
;                         lo = __builtin_amdgcn_cvt_pk_u8_f32(__builtin_rintf(v0[0] * 255.0f), 0, lo); lo = __builtin_amdgcn_cvt_pk_u8_f32(__builtin_rintf(v0[1] * 255.0f), 1, lo);
;                         lo = __builtin_amdgcn_cvt_pk_u8_f32(__builtin_rintf(v0[2] * 255.0f), 2, lo); lo = __builtin_amdgcn_cvt_pk_u8_f32(__builtin_rintf(v0[3] * 255.0f), 3, lo);
;                         hi = __builtin_amdgcn_cvt_pk_u8_f32(__builtin_rintf(v1[0] * 255.0f), 0, hi); hi = __builtin_amdgcn_cvt_pk_u8_f32(__builtin_rintf(v1[1] * 255.0f), 1, hi);
;                         hi = __builtin_amdgcn_cvt_pk_u8_f32(__builtin_rintf(v1[2] * 255.0f), 2, hi); hi = __builtin_amdgcn_cvt_pk_u8_f32(__builtin_rintf(v1[3] * 255.0f), 3, hi);
;                         if (bj == 0) { g8.x = lo; g8.y = hi; } else { g8.z = lo; g8.w = hi; } }
.LBB0_340:
	s_andn2_b64 vcc, exec, s[74:75]
	s_cbranch_vccnz .LBB0_344
	v_exp_f32_e32 v1, v98
	v_exp_f32_e32 v92, v92
	v_exp_f32_e32 v98, v99
	v_exp_f32_e32 v2, v2
	v_fmaak_f32 v1, v1, v247, 0x3b808081
	v_fmaak_f32 v92, v92, v247, 0x3b808081
	v_exp_f32_e32 v3, v3
	v_rcp_f32_e32 v1, v1
	v_rcp_f32_e32 v99, v92
	v_fmaak_f32 v92, v98, v247, 0x3b808081
	v_rcp_f32_e32 v92, v92
	v_fmaak_f32 v2, v2, v247, 0x3b808081
	v_exp_f32_e32 v93, v93
	v_rcp_f32_e32 v2, v2
	v_fmaak_f32 v3, v3, v247, 0x3b808081
	v_exp_f32_e32 v94, v94
	v_rcp_f32_e32 v3, v3
	v_rndne_f32_e32 v1, v1
	v_fmaak_f32 v93, v93, v247, 0x3b808081
	v_exp_f32_e32 v95, v95
	v_cvt_pk_u8_f32 v1, v1, 0, 0
	v_rndne_f32_e32 v92, v92
	v_rcp_f32_e32 v93, v93
	v_cvt_pk_u8_f32 v1, v92, 1, v1
	v_rndne_f32_e32 v2, v2
	v_fmaak_f32 v94, v94, v247, 0x3b808081
	v_cvt_pk_u8_f32 v1, v2, 2, v1
	v_rcp_f32_e32 v94, v94
	v_rndne_f32_e32 v2, v3
	v_fmaak_f32 v95, v95, v247, 0x3b808081
	v_cvt_pk_u8_f32 v92, v2, 3, v1
	v_rcp_f32_e32 v95, v95
	v_rndne_f32_e32 v1, v99
	v_cvt_pk_u8_f32 v1, v1, 0, 0
	v_rndne_f32_e32 v2, v93
	v_cvt_pk_u8_f32 v1, v2, 1, v1
	v_rndne_f32_e32 v2, v94
	v_cvt_pk_u8_f32 v1, v2, 2, v1
	v_rndne_f32_e32 v2, v95
	v_cvt_pk_u8_f32 v93, v2, 3, v1
	v_mov_b32_e32 v94, v0
	v_mov_b32_e32 v95, v0
	s_branch .LBB0_345

; __device__ __forceinline__ float sigmoid_f(float v) { return __builtin_amdgcn_rcpf(1.0f + __builtin_amdgcn_exp2f(-v * LOG2E)); }
;     __device__ __forceinline__ void operator()(f32x4 (&acc)[2][2][4][2], const Unit& u, int wr, int wc, int fr, int fq) const {
;     ...
;                     if (sig) {
; #pragma unroll
;                         for (int e = 0; e < 4; ++e) { v0[e] = sigmoid_f(v0[e]); v1[e] = sigmoid_f(v1[e]); }
;                         unsigned lo = 0u, hi = 0u;
;                         lo = __builtin_amdgcn_cvt_pk_u8_f32(__builtin_rintf(v0[0] * 255.0f), 0, lo); lo = __builtin_amdgcn_cvt_pk_u8_f32(__builtin_rintf(v0[1] * 255.0f), 1, lo);
;                         lo = __builtin_amdgcn_cvt_pk_u8_f32(__builtin_rintf(v0[2] * 255.0f), 2, lo); lo = __builtin_amdgcn_cvt_pk_u8_f32(__builtin_rintf(v0[3] * 255.0f), 3, lo);
;                         hi = __builtin_amdgcn_cvt_pk_u8_f32(__builtin_rintf(v1[0] * 255.0f), 0, hi); hi = __builtin_amdgcn_cvt_pk_u8_f32(__builtin_rintf(v1[1] * 255.0f), 1, hi);
;                         hi = __builtin_amdgcn_cvt_pk_u8_f32(__builtin_rintf(v1[2] * 255.0f), 2, hi); hi = __builtin_amdgcn_cvt_pk_u8_f32(__builtin_rintf(v1[3] * 255.0f), 3, hi);
;                         if (bj == 0) { g8.x = lo; g8.y = hi; } else { g8.z = lo; g8.w = hi; } }
.LBB0_343:
	v_exp_f32_e32 v1, v104
	v_exp_f32_e32 v104, v105
	v_exp_f32_e32 v2, v2
	v_fmaak_f32 v1, v1, v247, 0x3b808081
	v_exp_f32_e32 v3, v3
	v_rcp_f32_e32 v1, v1
	v_fmaak_f32 v104, v104, v247, 0x3b808081
	v_exp_f32_e32 v100, v100
	v_rcp_f32_e32 v104, v104
	v_fmaak_f32 v2, v2, v247, 0x3b808081
	v_exp_f32_e32 v101, v101
	v_rcp_f32_e32 v2, v2
	v_fmaak_f32 v3, v3, v247, 0x3b808081
	v_exp_f32_e32 v102, v102
	v_rcp_f32_e32 v3, v3
	v_fmaak_f32 v100, v100, v247, 0x3b808081
	v_rndne_f32_e32 v1, v1
	v_rcp_f32_e32 v100, v100
	v_fmaak_f32 v101, v101, v247, 0x3b808081
	v_exp_f32_e32 v103, v103
	v_cvt_pk_u8_f32 v1, v1, 0, 0
	v_rndne_f32_e32 v104, v104
	v_rcp_f32_e32 v101, v101
	v_cvt_pk_u8_f32 v1, v104, 1, v1
	v_rndne_f32_e32 v2, v2
	v_fmaak_f32 v102, v102, v247, 0x3b808081
	v_cvt_pk_u8_f32 v1, v2, 2, v1
	v_rcp_f32_e32 v102, v102
	v_rndne_f32_e32 v2, v3
	v_fmaak_f32 v103, v103, v247, 0x3b808081
	v_cvt_pk_u8_f32 v110, v2, 3, v1
	v_rcp_f32_e32 v103, v103
	v_rndne_f32_e32 v1, v100
	v_cvt_pk_u8_f32 v1, v1, 0, 0
	v_rndne_f32_e32 v2, v101
	v_cvt_pk_u8_f32 v1, v2, 1, v1
	v_rndne_f32_e32 v2, v102
	v_cvt_pk_u8_f32 v1, v2, 2, v1
	v_rndne_f32_e32 v2, v103
	v_cvt_pk_u8_f32 v111, v2, 3, v1
	s_and_b64 vcc, exec, s[6:7]
	s_cbranch_vccz .LBB0_337
	s_branch .LBB0_338

; __device__ __forceinline__ float sigmoid_f(float v) { return __builtin_amdgcn_rcpf(1.0f + __builtin_amdgcn_exp2f(-v * LOG2E)); }
;     __device__ __forceinline__ void operator()(f32x4 (&acc)[2][2][4][2], const Unit& u, int wr, int wc, int fr, int fq) const {
;     ...
;                     if (sig) {
; #pragma unroll
;                         for (int e = 0; e < 4; ++e) { v0[e] = sigmoid_f(v0[e]); v1[e] = sigmoid_f(v1[e]); }
;                         unsigned lo = 0u, hi = 0u;
;                         lo = __builtin_amdgcn_cvt_pk_u8_f32(__builtin_rintf(v0[0] * 255.0f), 0, lo); lo = __builtin_amdgcn_cvt_pk_u8_f32(__builtin_rintf(v0[1] * 255.0f), 1, lo);
;                         lo = __builtin_amdgcn_cvt_pk_u8_f32(__builtin_rintf(v0[2] * 255.0f), 2, lo); lo = __builtin_amdgcn_cvt_pk_u8_f32(__builtin_rintf(v0[3] * 255.0f), 3, lo);
;                         hi = __builtin_amdgcn_cvt_pk_u8_f32(__builtin_rintf(v1[0] * 255.0f), 0, hi); hi = __builtin_amdgcn_cvt_pk_u8_f32(__builtin_rintf(v1[1] * 255.0f), 1, hi);
;                         hi = __builtin_amdgcn_cvt_pk_u8_f32(__builtin_rintf(v1[2] * 255.0f), 2, hi); hi = __builtin_amdgcn_cvt_pk_u8_f32(__builtin_rintf(v1[3] * 255.0f), 3, hi);
;                         if (bj == 0) { g8.x = lo; g8.y = hi; } else { g8.z = lo; g8.w = hi; } }
.LBB0_351:
	s_andn2_b64 vcc, exec, s[74:75]
	s_cbranch_vccnz .LBB0_355
	v_exp_f32_e32 v1, v82
	v_exp_f32_e32 v76, v76
	v_exp_f32_e32 v82, v83
	v_exp_f32_e32 v2, v2
	v_fmaak_f32 v1, v1, v247, 0x3b808081
	v_fmaak_f32 v76, v76, v247, 0x3b808081
	v_exp_f32_e32 v3, v3
	v_rcp_f32_e32 v1, v1
	v_rcp_f32_e32 v83, v76
	v_fmaak_f32 v76, v82, v247, 0x3b808081
	v_rcp_f32_e32 v76, v76
	v_fmaak_f32 v2, v2, v247, 0x3b808081
	v_exp_f32_e32 v77, v77
	v_rcp_f32_e32 v2, v2
	v_fmaak_f32 v3, v3, v247, 0x3b808081
	v_exp_f32_e32 v78, v78
	v_rcp_f32_e32 v3, v3
	v_rndne_f32_e32 v1, v1
	v_fmaak_f32 v77, v77, v247, 0x3b808081
	v_exp_f32_e32 v79, v79
	v_cvt_pk_u8_f32 v1, v1, 0, 0
	v_rndne_f32_e32 v76, v76
	v_rcp_f32_e32 v77, v77
	v_cvt_pk_u8_f32 v1, v76, 1, v1
	v_rndne_f32_e32 v2, v2
	v_fmaak_f32 v78, v78, v247, 0x3b808081
	v_cvt_pk_u8_f32 v1, v2, 2, v1
	v_rcp_f32_e32 v78, v78
	v_rndne_f32_e32 v2, v3
	v_fmaak_f32 v79, v79, v247, 0x3b808081
	v_cvt_pk_u8_f32 v76, v2, 3, v1
	v_rcp_f32_e32 v79, v79
	v_rndne_f32_e32 v1, v83
	v_cvt_pk_u8_f32 v1, v1, 0, 0
	v_rndne_f32_e32 v2, v77
	v_cvt_pk_u8_f32 v1, v2, 1, v1
	v_rndne_f32_e32 v2, v78
	v_cvt_pk_u8_f32 v1, v2, 2, v1
	v_rndne_f32_e32 v2, v79
	v_cvt_pk_u8_f32 v77, v2, 3, v1
	v_mov_b32_e32 v78, v0
	v_mov_b32_e32 v79, v0
	s_branch .LBB0_356

; __device__ __forceinline__ float sigmoid_f(float v) { return __builtin_amdgcn_rcpf(1.0f + __builtin_amdgcn_exp2f(-v * LOG2E)); }
;     __device__ __forceinline__ void operator()(f32x4 (&acc)[2][2][4][2], const Unit& u, int wr, int wc, int fr, int fq) const {
;     ...
;                     if (sig) {
; #pragma unroll
;                         for (int e = 0; e < 4; ++e) { v0[e] = sigmoid_f(v0[e]); v1[e] = sigmoid_f(v1[e]); }
;                         unsigned lo = 0u, hi = 0u;
;                         lo = __builtin_amdgcn_cvt_pk_u8_f32(__builtin_rintf(v0[0] * 255.0f), 0, lo); lo = __builtin_amdgcn_cvt_pk_u8_f32(__builtin_rintf(v0[1] * 255.0f), 1, lo);
;                         lo = __builtin_amdgcn_cvt_pk_u8_f32(__builtin_rintf(v0[2] * 255.0f), 2, lo); lo = __builtin_amdgcn_cvt_pk_u8_f32(__builtin_rintf(v0[3] * 255.0f), 3, lo);
;                         hi = __builtin_amdgcn_cvt_pk_u8_f32(__builtin_rintf(v1[0] * 255.0f), 0, hi); hi = __builtin_amdgcn_cvt_pk_u8_f32(__builtin_rintf(v1[1] * 255.0f), 1, hi);
;                         hi = __builtin_amdgcn_cvt_pk_u8_f32(__builtin_rintf(v1[2] * 255.0f), 2, hi); hi = __builtin_amdgcn_cvt_pk_u8_f32(__builtin_rintf(v1[3] * 255.0f), 3, hi);
;                         if (bj == 0) { g8.x = lo; g8.y = hi; } else { g8.z = lo; g8.w = hi; } }
.LBB0_354:
	v_exp_f32_e32 v1, v88
	v_exp_f32_e32 v88, v89
	v_exp_f32_e32 v2, v2
	v_fmaak_f32 v1, v1, v247, 0x3b808081
	v_exp_f32_e32 v3, v3
	v_rcp_f32_e32 v1, v1
	v_fmaak_f32 v88, v88, v247, 0x3b808081
	v_exp_f32_e32 v84, v84
	v_rcp_f32_e32 v88, v88
	v_fmaak_f32 v2, v2, v247, 0x3b808081
	v_exp_f32_e32 v85, v85
	v_rcp_f32_e32 v2, v2
	v_fmaak_f32 v3, v3, v247, 0x3b808081
	v_exp_f32_e32 v86, v86
	v_rcp_f32_e32 v3, v3
	v_fmaak_f32 v84, v84, v247, 0x3b808081
	v_rndne_f32_e32 v1, v1
	v_rcp_f32_e32 v84, v84
	v_fmaak_f32 v85, v85, v247, 0x3b808081
	v_exp_f32_e32 v87, v87
	v_cvt_pk_u8_f32 v1, v1, 0, 0
	v_rndne_f32_e32 v88, v88
	v_rcp_f32_e32 v85, v85
	v_cvt_pk_u8_f32 v1, v88, 1, v1
	v_rndne_f32_e32 v2, v2
	v_fmaak_f32 v86, v86, v247, 0x3b808081
	v_cvt_pk_u8_f32 v1, v2, 2, v1
	v_rcp_f32_e32 v86, v86
	v_rndne_f32_e32 v2, v3
	v_fmaak_f32 v87, v87, v247, 0x3b808081
	v_cvt_pk_u8_f32 v94, v2, 3, v1
	v_rcp_f32_e32 v87, v87
	v_rndne_f32_e32 v1, v84
	v_cvt_pk_u8_f32 v1, v1, 0, 0
	v_rndne_f32_e32 v2, v85
	v_cvt_pk_u8_f32 v1, v2, 1, v1
	v_rndne_f32_e32 v2, v86
	v_cvt_pk_u8_f32 v1, v2, 2, v1
	v_rndne_f32_e32 v2, v87
	v_cvt_pk_u8_f32 v95, v2, 3, v1
	s_and_b64 vcc, exec, s[6:7]
	s_cbranch_vccz .LBB0_348
	s_branch .LBB0_349

; __device__ __forceinline__ float sigmoid_f(float v) { return __builtin_amdgcn_rcpf(1.0f + __builtin_amdgcn_exp2f(-v * LOG2E)); }
;     __device__ __forceinline__ void operator()(f32x4 (&acc)[2][2][4][2], const Unit& u, int wr, int wc, int fr, int fq) const {
;     ...
;                     if (sig) {
; #pragma unroll
;                         for (int e = 0; e < 4; ++e) { v0[e] = sigmoid_f(v0[e]); v1[e] = sigmoid_f(v1[e]); }
;                         unsigned lo = 0u, hi = 0u;
;                         lo = __builtin_amdgcn_cvt_pk_u8_f32(__builtin_rintf(v0[0] * 255.0f), 0, lo); lo = __builtin_amdgcn_cvt_pk_u8_f32(__builtin_rintf(v0[1] * 255.0f), 1, lo);
;                         lo = __builtin_amdgcn_cvt_pk_u8_f32(__builtin_rintf(v0[2] * 255.0f), 2, lo); lo = __builtin_amdgcn_cvt_pk_u8_f32(__builtin_rintf(v0[3] * 255.0f), 3, lo);
;                         hi = __builtin_amdgcn_cvt_pk_u8_f32(__builtin_rintf(v1[0] * 255.0f), 0, hi); hi = __builtin_amdgcn_cvt_pk_u8_f32(__builtin_rintf(v1[1] * 255.0f), 1, hi);
;                         hi = __builtin_amdgcn_cvt_pk_u8_f32(__builtin_rintf(v1[2] * 255.0f), 2, hi); hi = __builtin_amdgcn_cvt_pk_u8_f32(__builtin_rintf(v1[3] * 255.0f), 3, hi);
;                         if (bj == 0) { g8.x = lo; g8.y = hi; } else { g8.z = lo; g8.w = hi; } }
.LBB0_362:
	s_andn2_b64 vcc, exec, s[74:75]
	s_cbranch_vccnz .LBB0_366
	v_exp_f32_e32 v1, v66
	v_exp_f32_e32 v60, v60
	v_exp_f32_e32 v66, v67
	v_exp_f32_e32 v2, v2
	v_fmaak_f32 v1, v1, v247, 0x3b808081
	v_fmaak_f32 v60, v60, v247, 0x3b808081
	v_exp_f32_e32 v3, v3
	v_rcp_f32_e32 v1, v1
	v_rcp_f32_e32 v67, v60
	v_fmaak_f32 v60, v66, v247, 0x3b808081
	v_rcp_f32_e32 v60, v60
	v_fmaak_f32 v2, v2, v247, 0x3b808081
	v_exp_f32_e32 v61, v61
	v_rcp_f32_e32 v2, v2
	v_fmaak_f32 v3, v3, v247, 0x3b808081
	v_exp_f32_e32 v62, v62
	v_rcp_f32_e32 v3, v3
	v_rndne_f32_e32 v1, v1
	v_fmaak_f32 v61, v61, v247, 0x3b808081
	v_exp_f32_e32 v63, v63
	v_cvt_pk_u8_f32 v1, v1, 0, 0
	v_rndne_f32_e32 v60, v60
	v_rcp_f32_e32 v61, v61
	v_cvt_pk_u8_f32 v1, v60, 1, v1
	v_rndne_f32_e32 v2, v2
	v_fmaak_f32 v62, v62, v247, 0x3b808081
	v_cvt_pk_u8_f32 v1, v2, 2, v1
	v_rcp_f32_e32 v62, v62
	v_rndne_f32_e32 v2, v3
	v_fmaak_f32 v63, v63, v247, 0x3b808081
	v_cvt_pk_u8_f32 v60, v2, 3, v1
	v_rcp_f32_e32 v63, v63
	v_rndne_f32_e32 v1, v67
	v_cvt_pk_u8_f32 v1, v1, 0, 0
	v_rndne_f32_e32 v2, v61
	v_cvt_pk_u8_f32 v1, v2, 1, v1
	v_rndne_f32_e32 v2, v62
	v_cvt_pk_u8_f32 v1, v2, 2, v1
	v_rndne_f32_e32 v2, v63
	v_cvt_pk_u8_f32 v61, v2, 3, v1
	v_mov_b32_e32 v62, v0
	v_mov_b32_e32 v63, v0
	s_branch .LBB0_367

; __device__ __forceinline__ float sigmoid_f(float v) { return __builtin_amdgcn_rcpf(1.0f + __builtin_amdgcn_exp2f(-v * LOG2E)); }
;     __device__ __forceinline__ void operator()(f32x4 (&acc)[2][2][4][2], const Unit& u, int wr, int wc, int fr, int fq) const {
;     ...
;                     if (sig) {
; #pragma unroll
;                         for (int e = 0; e < 4; ++e) { v0[e] = sigmoid_f(v0[e]); v1[e] = sigmoid_f(v1[e]); }
;                         unsigned lo = 0u, hi = 0u;
;                         lo = __builtin_amdgcn_cvt_pk_u8_f32(__builtin_rintf(v0[0] * 255.0f), 0, lo); lo = __builtin_amdgcn_cvt_pk_u8_f32(__builtin_rintf(v0[1] * 255.0f), 1, lo);
;                         lo = __builtin_amdgcn_cvt_pk_u8_f32(__builtin_rintf(v0[2] * 255.0f), 2, lo); lo = __builtin_amdgcn_cvt_pk_u8_f32(__builtin_rintf(v0[3] * 255.0f), 3, lo);
;                         hi = __builtin_amdgcn_cvt_pk_u8_f32(__builtin_rintf(v1[0] * 255.0f), 0, hi); hi = __builtin_amdgcn_cvt_pk_u8_f32(__builtin_rintf(v1[1] * 255.0f), 1, hi);
;                         hi = __builtin_amdgcn_cvt_pk_u8_f32(__builtin_rintf(v1[2] * 255.0f), 2, hi); hi = __builtin_amdgcn_cvt_pk_u8_f32(__builtin_rintf(v1[3] * 255.0f), 3, hi);
;                         if (bj == 0) { g8.x = lo; g8.y = hi; } else { g8.z = lo; g8.w = hi; } }
.LBB0_365:
	v_exp_f32_e32 v1, v72
	v_exp_f32_e32 v72, v73
	v_exp_f32_e32 v2, v2
	v_fmaak_f32 v1, v1, v247, 0x3b808081
	v_exp_f32_e32 v3, v3
	v_rcp_f32_e32 v1, v1
	v_fmaak_f32 v72, v72, v247, 0x3b808081
	v_exp_f32_e32 v68, v68
	v_rcp_f32_e32 v72, v72
	v_fmaak_f32 v2, v2, v247, 0x3b808081
	v_exp_f32_e32 v69, v69
	v_rcp_f32_e32 v2, v2
	v_fmaak_f32 v3, v3, v247, 0x3b808081
	v_exp_f32_e32 v70, v70
	v_rcp_f32_e32 v3, v3
	v_fmaak_f32 v68, v68, v247, 0x3b808081
	v_rndne_f32_e32 v1, v1
	v_rcp_f32_e32 v68, v68
	v_fmaak_f32 v69, v69, v247, 0x3b808081
	v_exp_f32_e32 v71, v71
	v_cvt_pk_u8_f32 v1, v1, 0, 0
	v_rndne_f32_e32 v72, v72
	v_rcp_f32_e32 v69, v69
	v_cvt_pk_u8_f32 v1, v72, 1, v1
	v_rndne_f32_e32 v2, v2
	v_fmaak_f32 v70, v70, v247, 0x3b808081
	v_cvt_pk_u8_f32 v1, v2, 2, v1
	v_rcp_f32_e32 v70, v70
	v_rndne_f32_e32 v2, v3
	v_fmaak_f32 v71, v71, v247, 0x3b808081
	v_cvt_pk_u8_f32 v78, v2, 3, v1
	v_rcp_f32_e32 v71, v71
	v_rndne_f32_e32 v1, v68
	v_cvt_pk_u8_f32 v1, v1, 0, 0
	v_rndne_f32_e32 v2, v69
	v_cvt_pk_u8_f32 v1, v2, 1, v1
	v_rndne_f32_e32 v2, v70
	v_cvt_pk_u8_f32 v1, v2, 2, v1
	v_rndne_f32_e32 v2, v71
	v_cvt_pk_u8_f32 v79, v2, 3, v1
	s_and_b64 vcc, exec, s[6:7]
	s_cbranch_vccz .LBB0_359
	s_branch .LBB0_360

; __device__ __forceinline__ float sigmoid_f(float v) { return __builtin_amdgcn_rcpf(1.0f + __builtin_amdgcn_exp2f(-v * LOG2E)); }
;     __device__ __forceinline__ void operator()(f32x4 (&acc)[2][2][4][2], const Unit& u, int wr, int wc, int fr, int fq) const {
;     ...
;                     if (sig) {
; #pragma unroll
;                         for (int e = 0; e < 4; ++e) { v0[e] = sigmoid_f(v0[e]); v1[e] = sigmoid_f(v1[e]); }
;                         unsigned lo = 0u, hi = 0u;
;                         lo = __builtin_amdgcn_cvt_pk_u8_f32(__builtin_rintf(v0[0] * 255.0f), 0, lo); lo = __builtin_amdgcn_cvt_pk_u8_f32(__builtin_rintf(v0[1] * 255.0f), 1, lo);
;                         lo = __builtin_amdgcn_cvt_pk_u8_f32(__builtin_rintf(v0[2] * 255.0f), 2, lo); lo = __builtin_amdgcn_cvt_pk_u8_f32(__builtin_rintf(v0[3] * 255.0f), 3, lo);
;                         hi = __builtin_amdgcn_cvt_pk_u8_f32(__builtin_rintf(v1[0] * 255.0f), 0, hi); hi = __builtin_amdgcn_cvt_pk_u8_f32(__builtin_rintf(v1[1] * 255.0f), 1, hi);
;                         hi = __builtin_amdgcn_cvt_pk_u8_f32(__builtin_rintf(v1[2] * 255.0f), 2, hi); hi = __builtin_amdgcn_cvt_pk_u8_f32(__builtin_rintf(v1[3] * 255.0f), 3, hi);
;                         if (bj == 0) { g8.x = lo; g8.y = hi; } else { g8.z = lo; g8.w = hi; } }
.LBB0_373:
	s_andn2_b64 vcc, exec, s[74:75]
	s_cbranch_vccnz .LBB0_377
	v_exp_f32_e32 v1, v50
	v_exp_f32_e32 v44, v44
	v_exp_f32_e32 v50, v51
	v_exp_f32_e32 v2, v2
	v_fmaak_f32 v1, v1, v247, 0x3b808081
	v_fmaak_f32 v44, v44, v247, 0x3b808081
	v_exp_f32_e32 v3, v3
	v_rcp_f32_e32 v1, v1
	v_rcp_f32_e32 v51, v44
	v_fmaak_f32 v44, v50, v247, 0x3b808081
	v_rcp_f32_e32 v44, v44
	v_fmaak_f32 v2, v2, v247, 0x3b808081
	v_exp_f32_e32 v45, v45
	v_rcp_f32_e32 v2, v2
	v_fmaak_f32 v3, v3, v247, 0x3b808081
	v_exp_f32_e32 v46, v46
	v_rcp_f32_e32 v3, v3
	v_rndne_f32_e32 v1, v1
	v_fmaak_f32 v45, v45, v247, 0x3b808081
	v_exp_f32_e32 v47, v47
	v_cvt_pk_u8_f32 v1, v1, 0, 0
	v_rndne_f32_e32 v44, v44
	v_rcp_f32_e32 v45, v45
	v_cvt_pk_u8_f32 v1, v44, 1, v1
	v_rndne_f32_e32 v2, v2
	v_fmaak_f32 v46, v46, v247, 0x3b808081
	v_cvt_pk_u8_f32 v1, v2, 2, v1
	v_rcp_f32_e32 v46, v46
	v_rndne_f32_e32 v2, v3
	v_fmaak_f32 v47, v47, v247, 0x3b808081
	v_cvt_pk_u8_f32 v44, v2, 3, v1
	v_rcp_f32_e32 v47, v47
	v_rndne_f32_e32 v1, v51
	v_cvt_pk_u8_f32 v1, v1, 0, 0
	v_rndne_f32_e32 v2, v45
	v_cvt_pk_u8_f32 v1, v2, 1, v1
	v_rndne_f32_e32 v2, v46
	v_cvt_pk_u8_f32 v1, v2, 2, v1
	v_rndne_f32_e32 v2, v47
	v_cvt_pk_u8_f32 v45, v2, 3, v1
	v_mov_b32_e32 v46, v0
	v_mov_b32_e32 v47, v0
	s_branch .LBB0_378

; __device__ __forceinline__ float sigmoid_f(float v) { return __builtin_amdgcn_rcpf(1.0f + __builtin_amdgcn_exp2f(-v * LOG2E)); }
;     __device__ __forceinline__ void operator()(f32x4 (&acc)[2][2][4][2], const Unit& u, int wr, int wc, int fr, int fq) const {
;     ...
;                     if (sig) {
; #pragma unroll
;                         for (int e = 0; e < 4; ++e) { v0[e] = sigmoid_f(v0[e]); v1[e] = sigmoid_f(v1[e]); }
;                         unsigned lo = 0u, hi = 0u;
;                         lo = __builtin_amdgcn_cvt_pk_u8_f32(__builtin_rintf(v0[0] * 255.0f), 0, lo); lo = __builtin_amdgcn_cvt_pk_u8_f32(__builtin_rintf(v0[1] * 255.0f), 1, lo);
;                         lo = __builtin_amdgcn_cvt_pk_u8_f32(__builtin_rintf(v0[2] * 255.0f), 2, lo); lo = __builtin_amdgcn_cvt_pk_u8_f32(__builtin_rintf(v0[3] * 255.0f), 3, lo);
;                         hi = __builtin_amdgcn_cvt_pk_u8_f32(__builtin_rintf(v1[0] * 255.0f), 0, hi); hi = __builtin_amdgcn_cvt_pk_u8_f32(__builtin_rintf(v1[1] * 255.0f), 1, hi);
;                         hi = __builtin_amdgcn_cvt_pk_u8_f32(__builtin_rintf(v1[2] * 255.0f), 2, hi); hi = __builtin_amdgcn_cvt_pk_u8_f32(__builtin_rintf(v1[3] * 255.0f), 3, hi);
;                         if (bj == 0) { g8.x = lo; g8.y = hi; } else { g8.z = lo; g8.w = hi; } }
.LBB0_376:
	v_exp_f32_e32 v1, v56
	v_exp_f32_e32 v56, v57
	v_exp_f32_e32 v2, v2
	v_fmaak_f32 v1, v1, v247, 0x3b808081
	v_exp_f32_e32 v3, v3
	v_rcp_f32_e32 v1, v1
	v_fmaak_f32 v56, v56, v247, 0x3b808081
	v_exp_f32_e32 v52, v52
	v_rcp_f32_e32 v56, v56
	v_fmaak_f32 v2, v2, v247, 0x3b808081
	v_exp_f32_e32 v53, v53
	v_rcp_f32_e32 v2, v2
	v_fmaak_f32 v3, v3, v247, 0x3b808081
	v_exp_f32_e32 v54, v54
	v_rcp_f32_e32 v3, v3
	v_fmaak_f32 v52, v52, v247, 0x3b808081
	v_rndne_f32_e32 v1, v1
	v_rcp_f32_e32 v52, v52
	v_fmaak_f32 v53, v53, v247, 0x3b808081
	v_exp_f32_e32 v55, v55
	v_cvt_pk_u8_f32 v1, v1, 0, 0
	v_rndne_f32_e32 v56, v56
	v_rcp_f32_e32 v53, v53
	v_cvt_pk_u8_f32 v1, v56, 1, v1
	v_rndne_f32_e32 v2, v2
	v_fmaak_f32 v54, v54, v247, 0x3b808081
	v_cvt_pk_u8_f32 v1, v2, 2, v1
	v_rcp_f32_e32 v54, v54
	v_rndne_f32_e32 v2, v3
	v_fmaak_f32 v55, v55, v247, 0x3b808081
	v_cvt_pk_u8_f32 v62, v2, 3, v1
	v_rcp_f32_e32 v55, v55
	v_rndne_f32_e32 v1, v52
	v_cvt_pk_u8_f32 v1, v1, 0, 0
	v_rndne_f32_e32 v2, v53
	v_cvt_pk_u8_f32 v1, v2, 1, v1
	v_rndne_f32_e32 v2, v54
	v_cvt_pk_u8_f32 v1, v2, 2, v1
	v_rndne_f32_e32 v2, v55
	v_cvt_pk_u8_f32 v63, v2, 3, v1
	s_and_b64 vcc, exec, s[6:7]
	s_cbranch_vccz .LBB0_370
	s_branch .LBB0_371

; __device__ __forceinline__ float sigmoid_f(float v) { return __builtin_amdgcn_rcpf(1.0f + __builtin_amdgcn_exp2f(-v * LOG2E)); }
;     __device__ __forceinline__ void operator()(f32x4 (&acc)[2][2][4][2], const Unit& u, int wr, int wc, int fr, int fq) const {
;     ...
;                     if (sig) {
; #pragma unroll
;                         for (int e = 0; e < 4; ++e) { v0[e] = sigmoid_f(v0[e]); v1[e] = sigmoid_f(v1[e]); }
;                         unsigned lo = 0u, hi = 0u;
;                         lo = __builtin_amdgcn_cvt_pk_u8_f32(__builtin_rintf(v0[0] * 255.0f), 0, lo); lo = __builtin_amdgcn_cvt_pk_u8_f32(__builtin_rintf(v0[1] * 255.0f), 1, lo);
;                         lo = __builtin_amdgcn_cvt_pk_u8_f32(__builtin_rintf(v0[2] * 255.0f), 2, lo); lo = __builtin_amdgcn_cvt_pk_u8_f32(__builtin_rintf(v0[3] * 255.0f), 3, lo);
;                         hi = __builtin_amdgcn_cvt_pk_u8_f32(__builtin_rintf(v1[0] * 255.0f), 0, hi); hi = __builtin_amdgcn_cvt_pk_u8_f32(__builtin_rintf(v1[1] * 255.0f), 1, hi);
;                         hi = __builtin_amdgcn_cvt_pk_u8_f32(__builtin_rintf(v1[2] * 255.0f), 2, hi); hi = __builtin_amdgcn_cvt_pk_u8_f32(__builtin_rintf(v1[3] * 255.0f), 3, hi);
;                         if (bj == 0) { g8.x = lo; g8.y = hi; } else { g8.z = lo; g8.w = hi; } }
.LBB0_384:
	s_andn2_b64 vcc, exec, s[74:75]
	s_cbranch_vccnz .LBB0_388
	v_exp_f32_e32 v1, v34
	v_exp_f32_e32 v28, v28
	v_exp_f32_e32 v34, v35
	v_exp_f32_e32 v2, v2
	v_fmaak_f32 v1, v1, v247, 0x3b808081
	v_fmaak_f32 v28, v28, v247, 0x3b808081
	v_exp_f32_e32 v3, v3
	v_rcp_f32_e32 v1, v1
	v_rcp_f32_e32 v35, v28
	v_fmaak_f32 v28, v34, v247, 0x3b808081
	v_rcp_f32_e32 v28, v28
	v_fmaak_f32 v2, v2, v247, 0x3b808081
	v_exp_f32_e32 v29, v29
	v_rcp_f32_e32 v2, v2
	v_fmaak_f32 v3, v3, v247, 0x3b808081
	v_exp_f32_e32 v30, v30
	v_rcp_f32_e32 v3, v3
	v_rndne_f32_e32 v1, v1
	v_fmaak_f32 v29, v29, v247, 0x3b808081
	v_exp_f32_e32 v31, v31
	v_cvt_pk_u8_f32 v1, v1, 0, 0
	v_rndne_f32_e32 v28, v28
	v_rcp_f32_e32 v29, v29
	v_cvt_pk_u8_f32 v1, v28, 1, v1
	v_rndne_f32_e32 v2, v2
	v_fmaak_f32 v30, v30, v247, 0x3b808081
	v_cvt_pk_u8_f32 v1, v2, 2, v1
	v_rcp_f32_e32 v30, v30
	v_rndne_f32_e32 v2, v3
	v_fmaak_f32 v31, v31, v247, 0x3b808081
	v_cvt_pk_u8_f32 v28, v2, 3, v1
	v_rcp_f32_e32 v31, v31
	v_rndne_f32_e32 v1, v35
	v_cvt_pk_u8_f32 v1, v1, 0, 0
	v_rndne_f32_e32 v2, v29
	v_cvt_pk_u8_f32 v1, v2, 1, v1
	v_rndne_f32_e32 v2, v30
	v_cvt_pk_u8_f32 v1, v2, 2, v1
	v_rndne_f32_e32 v2, v31
	v_cvt_pk_u8_f32 v29, v2, 3, v1
	v_mov_b32_e32 v30, v0
	v_mov_b32_e32 v31, v0
	s_branch .LBB0_389

; __device__ __forceinline__ float sigmoid_f(float v) { return __builtin_amdgcn_rcpf(1.0f + __builtin_amdgcn_exp2f(-v * LOG2E)); }
;     __device__ __forceinline__ void operator()(f32x4 (&acc)[2][2][4][2], const Unit& u, int wr, int wc, int fr, int fq) const {
;     ...
;                     if (sig) {
; #pragma unroll
;                         for (int e = 0; e < 4; ++e) { v0[e] = sigmoid_f(v0[e]); v1[e] = sigmoid_f(v1[e]); }
;                         unsigned lo = 0u, hi = 0u;
;                         lo = __builtin_amdgcn_cvt_pk_u8_f32(__builtin_rintf(v0[0] * 255.0f), 0, lo); lo = __builtin_amdgcn_cvt_pk_u8_f32(__builtin_rintf(v0[1] * 255.0f), 1, lo);
;                         lo = __builtin_amdgcn_cvt_pk_u8_f32(__builtin_rintf(v0[2] * 255.0f), 2, lo); lo = __builtin_amdgcn_cvt_pk_u8_f32(__builtin_rintf(v0[3] * 255.0f), 3, lo);
;                         hi = __builtin_amdgcn_cvt_pk_u8_f32(__builtin_rintf(v1[0] * 255.0f), 0, hi); hi = __builtin_amdgcn_cvt_pk_u8_f32(__builtin_rintf(v1[1] * 255.0f), 1, hi);
;                         hi = __builtin_amdgcn_cvt_pk_u8_f32(__builtin_rintf(v1[2] * 255.0f), 2, hi); hi = __builtin_amdgcn_cvt_pk_u8_f32(__builtin_rintf(v1[3] * 255.0f), 3, hi);
;                         if (bj == 0) { g8.x = lo; g8.y = hi; } else { g8.z = lo; g8.w = hi; } }
.LBB0_387:
	v_exp_f32_e32 v1, v40
	v_exp_f32_e32 v40, v41
	v_exp_f32_e32 v2, v2
	v_fmaak_f32 v1, v1, v247, 0x3b808081
	v_exp_f32_e32 v3, v3
	v_rcp_f32_e32 v1, v1
	v_fmaak_f32 v40, v40, v247, 0x3b808081
	v_exp_f32_e32 v36, v36
	v_rcp_f32_e32 v40, v40
	v_fmaak_f32 v2, v2, v247, 0x3b808081
	v_exp_f32_e32 v37, v37
	v_rcp_f32_e32 v2, v2
	v_fmaak_f32 v3, v3, v247, 0x3b808081
	v_exp_f32_e32 v38, v38
	v_rcp_f32_e32 v3, v3
	v_fmaak_f32 v36, v36, v247, 0x3b808081
	v_rndne_f32_e32 v1, v1
	v_rcp_f32_e32 v36, v36
	v_fmaak_f32 v37, v37, v247, 0x3b808081
	v_exp_f32_e32 v39, v39
	v_cvt_pk_u8_f32 v1, v1, 0, 0
	v_rndne_f32_e32 v40, v40
	v_rcp_f32_e32 v37, v37
	v_cvt_pk_u8_f32 v1, v40, 1, v1
	v_rndne_f32_e32 v2, v2
	v_fmaak_f32 v38, v38, v247, 0x3b808081
	v_cvt_pk_u8_f32 v1, v2, 2, v1
	v_rcp_f32_e32 v38, v38
	v_rndne_f32_e32 v2, v3
	v_fmaak_f32 v39, v39, v247, 0x3b808081
	v_cvt_pk_u8_f32 v46, v2, 3, v1
	v_rcp_f32_e32 v39, v39
	v_rndne_f32_e32 v1, v36
	v_cvt_pk_u8_f32 v1, v1, 0, 0
	v_rndne_f32_e32 v2, v37
	v_cvt_pk_u8_f32 v1, v2, 1, v1
	v_rndne_f32_e32 v2, v38
	v_cvt_pk_u8_f32 v1, v2, 2, v1
	v_rndne_f32_e32 v2, v39
	v_cvt_pk_u8_f32 v47, v2, 3, v1
	s_and_b64 vcc, exec, s[6:7]
	s_cbranch_vccz .LBB0_381
	s_branch .LBB0_382

; __device__ __forceinline__ float sigmoid_f(float v) { return __builtin_amdgcn_rcpf(1.0f + __builtin_amdgcn_exp2f(-v * LOG2E)); }
;     __device__ __forceinline__ void operator()(f32x4 (&acc)[2][2][4][2], const Unit& u, int wr, int wc, int fr, int fq) const {
;     ...
;                     if (sig) {
; #pragma unroll
;                         for (int e = 0; e < 4; ++e) { v0[e] = sigmoid_f(v0[e]); v1[e] = sigmoid_f(v1[e]); }
;                         unsigned lo = 0u, hi = 0u;
;                         lo = __builtin_amdgcn_cvt_pk_u8_f32(__builtin_rintf(v0[0] * 255.0f), 0, lo); lo = __builtin_amdgcn_cvt_pk_u8_f32(__builtin_rintf(v0[1] * 255.0f), 1, lo);
;                         lo = __builtin_amdgcn_cvt_pk_u8_f32(__builtin_rintf(v0[2] * 255.0f), 2, lo); lo = __builtin_amdgcn_cvt_pk_u8_f32(__builtin_rintf(v0[3] * 255.0f), 3, lo);
;                         hi = __builtin_amdgcn_cvt_pk_u8_f32(__builtin_rintf(v1[0] * 255.0f), 0, hi); hi = __builtin_amdgcn_cvt_pk_u8_f32(__builtin_rintf(v1[1] * 255.0f), 1, hi);
;                         hi = __builtin_amdgcn_cvt_pk_u8_f32(__builtin_rintf(v1[2] * 255.0f), 2, hi); hi = __builtin_amdgcn_cvt_pk_u8_f32(__builtin_rintf(v1[3] * 255.0f), 3, hi);
;                         if (bj == 0) { g8.x = lo; g8.y = hi; } else { g8.z = lo; g8.w = hi; } }
.LBB0_395:
	s_andn2_b64 vcc, exec, s[74:75]
	s_cbranch_vccnz .LBB0_399
	v_exp_f32_e32 v1, v18
	v_exp_f32_e32 v12, v12
	v_exp_f32_e32 v18, v19
	v_exp_f32_e32 v2, v2
	v_fmaak_f32 v1, v1, v247, 0x3b808081
	v_fmaak_f32 v12, v12, v247, 0x3b808081
	v_exp_f32_e32 v3, v3
	v_rcp_f32_e32 v1, v1
	v_rcp_f32_e32 v19, v12
	v_fmaak_f32 v12, v18, v247, 0x3b808081
	v_rcp_f32_e32 v12, v12
	v_fmaak_f32 v2, v2, v247, 0x3b808081
	v_exp_f32_e32 v13, v13
	v_rcp_f32_e32 v2, v2
	v_fmaak_f32 v3, v3, v247, 0x3b808081
	v_exp_f32_e32 v14, v14
	v_rcp_f32_e32 v3, v3
	v_rndne_f32_e32 v1, v1
	v_fmaak_f32 v13, v13, v247, 0x3b808081
	v_exp_f32_e32 v15, v15
	v_cvt_pk_u8_f32 v1, v1, 0, 0
	v_rndne_f32_e32 v12, v12
	v_rcp_f32_e32 v13, v13
	v_cvt_pk_u8_f32 v1, v12, 1, v1
	v_rndne_f32_e32 v2, v2
	v_fmaak_f32 v14, v14, v247, 0x3b808081
	v_cvt_pk_u8_f32 v1, v2, 2, v1
	v_rcp_f32_e32 v14, v14
	v_rndne_f32_e32 v2, v3
	v_fmaak_f32 v15, v15, v247, 0x3b808081
	v_cvt_pk_u8_f32 v12, v2, 3, v1
	v_rcp_f32_e32 v15, v15
	v_rndne_f32_e32 v1, v19
	v_cvt_pk_u8_f32 v1, v1, 0, 0
	v_rndne_f32_e32 v2, v13
	v_cvt_pk_u8_f32 v1, v2, 1, v1
	v_rndne_f32_e32 v2, v14
	v_cvt_pk_u8_f32 v1, v2, 2, v1
	v_rndne_f32_e32 v2, v15
	v_cvt_pk_u8_f32 v13, v2, 3, v1
	v_mov_b32_e32 v14, v0
	v_mov_b32_e32 v15, v0
	s_branch .LBB0_400

; __device__ __forceinline__ float sigmoid_f(float v) { return __builtin_amdgcn_rcpf(1.0f + __builtin_amdgcn_exp2f(-v * LOG2E)); }
;     __device__ __forceinline__ void operator()(f32x4 (&acc)[2][2][4][2], const Unit& u, int wr, int wc, int fr, int fq) const {
;     ...
;                     if (sig) {
; #pragma unroll
;                         for (int e = 0; e < 4; ++e) { v0[e] = sigmoid_f(v0[e]); v1[e] = sigmoid_f(v1[e]); }
;                         unsigned lo = 0u, hi = 0u;
;                         lo = __builtin_amdgcn_cvt_pk_u8_f32(__builtin_rintf(v0[0] * 255.0f), 0, lo); lo = __builtin_amdgcn_cvt_pk_u8_f32(__builtin_rintf(v0[1] * 255.0f), 1, lo);
;                         lo = __builtin_amdgcn_cvt_pk_u8_f32(__builtin_rintf(v0[2] * 255.0f), 2, lo); lo = __builtin_amdgcn_cvt_pk_u8_f32(__builtin_rintf(v0[3] * 255.0f), 3, lo);
;                         hi = __builtin_amdgcn_cvt_pk_u8_f32(__builtin_rintf(v1[0] * 255.0f), 0, hi); hi = __builtin_amdgcn_cvt_pk_u8_f32(__builtin_rintf(v1[1] * 255.0f), 1, hi);
;                         hi = __builtin_amdgcn_cvt_pk_u8_f32(__builtin_rintf(v1[2] * 255.0f), 2, hi); hi = __builtin_amdgcn_cvt_pk_u8_f32(__builtin_rintf(v1[3] * 255.0f), 3, hi);
;                         if (bj == 0) { g8.x = lo; g8.y = hi; } else { g8.z = lo; g8.w = hi; } }
.LBB0_398:
	v_exp_f32_e32 v1, v24
	v_exp_f32_e32 v24, v25
	v_exp_f32_e32 v2, v2
	v_fmaak_f32 v1, v1, v247, 0x3b808081
	v_exp_f32_e32 v3, v3
	v_rcp_f32_e32 v1, v1
	v_fmaak_f32 v24, v24, v247, 0x3b808081
	v_exp_f32_e32 v20, v20
	v_rcp_f32_e32 v24, v24
	v_fmaak_f32 v2, v2, v247, 0x3b808081
	v_exp_f32_e32 v21, v21
	v_rcp_f32_e32 v2, v2
	v_fmaak_f32 v3, v3, v247, 0x3b808081
	v_exp_f32_e32 v22, v22
	v_rcp_f32_e32 v3, v3
	v_fmaak_f32 v20, v20, v247, 0x3b808081
	v_rndne_f32_e32 v1, v1
	v_rcp_f32_e32 v20, v20
	v_fmaak_f32 v21, v21, v247, 0x3b808081
	v_exp_f32_e32 v23, v23
	v_cvt_pk_u8_f32 v1, v1, 0, 0
	v_rndne_f32_e32 v24, v24
	v_rcp_f32_e32 v21, v21
	v_cvt_pk_u8_f32 v1, v24, 1, v1
	v_rndne_f32_e32 v2, v2
	v_fmaak_f32 v22, v22, v247, 0x3b808081
	v_cvt_pk_u8_f32 v1, v2, 2, v1
	v_rcp_f32_e32 v22, v22
	v_rndne_f32_e32 v2, v3
	v_fmaak_f32 v23, v23, v247, 0x3b808081
	v_cvt_pk_u8_f32 v30, v2, 3, v1
	v_rcp_f32_e32 v23, v23
	v_rndne_f32_e32 v1, v20
	v_cvt_pk_u8_f32 v1, v1, 0, 0
	v_rndne_f32_e32 v2, v21
	v_cvt_pk_u8_f32 v1, v2, 1, v1
	v_rndne_f32_e32 v2, v22
	v_cvt_pk_u8_f32 v1, v2, 2, v1
	v_rndne_f32_e32 v2, v23
	v_cvt_pk_u8_f32 v31, v2, 3, v1
	s_and_b64 vcc, exec, s[6:7]
	s_cbranch_vccz .LBB0_392
	s_branch .LBB0_393

; __device__ __forceinline__ float sigmoid_f(float v) { return __builtin_amdgcn_rcpf(1.0f + __builtin_amdgcn_exp2f(-v * LOG2E)); }
;     __device__ __forceinline__ void operator()(f32x4 (&acc)[2][2][4][2], const Unit& u, int wr, int wc, int fr, int fq) const {
;     ...
;                     if (sig) {
; #pragma unroll
;                         for (int e = 0; e < 4; ++e) { v0[e] = sigmoid_f(v0[e]); v1[e] = sigmoid_f(v1[e]); }
;                         unsigned lo = 0u, hi = 0u;
;                         lo = __builtin_amdgcn_cvt_pk_u8_f32(__builtin_rintf(v0[0] * 255.0f), 0, lo); lo = __builtin_amdgcn_cvt_pk_u8_f32(__builtin_rintf(v0[1] * 255.0f), 1, lo);
;                         lo = __builtin_amdgcn_cvt_pk_u8_f32(__builtin_rintf(v0[2] * 255.0f), 2, lo); lo = __builtin_amdgcn_cvt_pk_u8_f32(__builtin_rintf(v0[3] * 255.0f), 3, lo);
;                         hi = __builtin_amdgcn_cvt_pk_u8_f32(__builtin_rintf(v1[0] * 255.0f), 0, hi); hi = __builtin_amdgcn_cvt_pk_u8_f32(__builtin_rintf(v1[1] * 255.0f), 1, hi);
;                         hi = __builtin_amdgcn_cvt_pk_u8_f32(__builtin_rintf(v1[2] * 255.0f), 2, hi); hi = __builtin_amdgcn_cvt_pk_u8_f32(__builtin_rintf(v1[3] * 255.0f), 3, hi);
;                         if (bj == 0) { g8.x = lo; g8.y = hi; } else { g8.z = lo; g8.w = hi; } }
.LBB0_405:
	v_exp_f32_e32 v1, v8
	v_exp_f32_e32 v8, v9
	v_exp_f32_e32 v2, v2
	v_fmaak_f32 v1, v1, v247, 0x3b808081
	v_exp_f32_e32 v3, v3
	v_rcp_f32_e32 v1, v1
	v_fmaak_f32 v8, v8, v247, 0x3b808081
	v_exp_f32_e32 v4, v4
	v_rcp_f32_e32 v8, v8
	v_fmaak_f32 v2, v2, v247, 0x3b808081
	v_exp_f32_e32 v5, v5
	v_rcp_f32_e32 v2, v2
	v_fmaak_f32 v3, v3, v247, 0x3b808081
	v_exp_f32_e32 v6, v6
	v_rcp_f32_e32 v3, v3
	v_fmaak_f32 v4, v4, v247, 0x3b808081
	v_rndne_f32_e32 v1, v1
	v_rcp_f32_e32 v4, v4
	v_fmaak_f32 v5, v5, v247, 0x3b808081
	v_exp_f32_e32 v7, v7
	v_cvt_pk_u8_f32 v1, v1, 0, 0
	v_rndne_f32_e32 v8, v8
	v_rcp_f32_e32 v5, v5
	v_cvt_pk_u8_f32 v1, v8, 1, v1
	v_rndne_f32_e32 v2, v2
	v_fmaak_f32 v6, v6, v247, 0x3b808081
	v_cvt_pk_u8_f32 v1, v2, 2, v1
	v_rcp_f32_e32 v6, v6
	v_rndne_f32_e32 v2, v3
	v_fmaak_f32 v7, v7, v247, 0x3b808081
	v_cvt_pk_u8_f32 v14, v2, 3, v1
	v_rcp_f32_e32 v7, v7
	v_rndne_f32_e32 v1, v4
	v_cvt_pk_u8_f32 v1, v1, 0, 0
	v_rndne_f32_e32 v2, v5
	v_cvt_pk_u8_f32 v1, v2, 1, v1
	v_rndne_f32_e32 v2, v6
	v_cvt_pk_u8_f32 v1, v2, 2, v1
	v_rndne_f32_e32 v2, v7
	v_cvt_pk_u8_f32 v15, v2, 3, v1
	s_and_b64 vcc, exec, s[6:7]
	s_cbranch_vccnz .LBB0_403

; __global__ void __launch_bounds__(NTHR, 2) mk_fwd(Args args) {
	.amdhsa_kernel _Z6mk_fwd4Args
		.amdhsa_group_segment_fixed_size 0
		.amdhsa_private_segment_fixed_size 0
		.amdhsa_kernarg_size 408
		.amdhsa_user_sgpr_count 2
		.amdhsa_user_sgpr_dispatch_ptr 0
		.amdhsa_user_sgpr_queue_ptr 0
		.amdhsa_user_sgpr_kernarg_segment_ptr 1
		.amdhsa_user_sgpr_dispatch_id 0
		.amdhsa_user_sgpr_kernarg_preload_length 0
		.amdhsa_user_sgpr_kernarg_preload_offset 0
		.amdhsa_user_sgpr_private_segment_size 0
		.amdhsa_uses_dynamic_stack 0
		.amdhsa_enable_private_segment 0
		.amdhsa_system_sgpr_workgroup_id_x 1
		.amdhsa_system_sgpr_workgroup_id_y 0
		.amdhsa_system_sgpr_workgroup_id_z 0
		.amdhsa_system_sgpr_workgroup_info 0
		.amdhsa_system_vgpr_workitem_id 2
		.amdhsa_next_free_vgpr 249
		.amdhsa_next_free_sgpr 102
		.amdhsa_accum_offset 252
		.amdhsa_reserve_vcc 1
		.amdhsa_float_round_mode_32 0
		.amdhsa_float_round_mode_16_64 0
		.amdhsa_float_denorm_mode_32 3
		.amdhsa_float_denorm_mode_16_64 3
		.amdhsa_dx10_clamp 1
		.amdhsa_ieee_mode 1
		.amdhsa_fp16_overflow 0
		.amdhsa_tg_split 0
		.amdhsa_exception_fp_ieee_invalid_op 0
		.amdhsa_exception_fp_denorm_src 0
		.amdhsa_exception_fp_ieee_div_zero 0
		.amdhsa_exception_fp_ieee_overflow 0
		.amdhsa_exception_fp_ieee_underflow 0
		.amdhsa_exception_fp_ieee_inexact 0
		.amdhsa_exception_int_div_zero 0
	.end_amdhsa_kernel

; __global__ void __launch_bounds__(NTHR, 2) mk_fwd(Args args) {
amdhsa.kernels:
  - .agpr_count:     0
    .args:
      - .offset:         0
        .size:           152
        .value_kind:     by_value
      - .offset:         152
        .size:           4
        .value_kind:     hidden_block_count_x
      - .offset:         156
        .size:           4
        .value_kind:     hidden_block_count_y
      - .offset:         160
        .size:           4
        .value_kind:     hidden_block_count_z
      - .offset:         164
        .size:           2
        .value_kind:     hidden_group_size_x
      - .offset:         166
        .size:           2
        .value_kind:     hidden_group_size_y
      - .offset:         168
        .size:           2
        .value_kind:     hidden_group_size_z
      - .offset:         170
        .size:           2
        .value_kind:     hidden_remainder_x
      - .offset:         172
        .size:           2
        .value_kind:     hidden_remainder_y
      - .offset:         174
        .size:           2
        .value_kind:     hidden_remainder_z
      - .offset:         192
        .size:           8
        .value_kind:     hidden_global_offset_x
      - .offset:         200
        .size:           8
        .value_kind:     hidden_global_offset_y
      - .offset:         208
        .size:           8
        .value_kind:     hidden_global_offset_z
      - .offset:         216
        .size:           2
        .value_kind:     hidden_grid_dims
      - .offset:         240
        .size:           8
        .value_kind:     hidden_multigrid_sync_arg
      - .offset:         272
        .size:           4
        .value_kind:     hidden_dynamic_lds_size
    .group_segment_fixed_size: 0
    .kernarg_segment_align: 8
    .kernarg_segment_size: 408
    .language:       OpenCL C
    .language_version:
      - 2
      - 0
    .max_flat_workgroup_size: 512
    .name:           _Z6mk_fwd4Args
    .private_segment_fixed_size: 0
    .sgpr_count:     108
    .sgpr_spill_count: 12
    .symbol:         _Z6mk_fwd4Args.kd
    .uniform_work_group_size: 1
    .uses_dynamic_stack: false
    .vgpr_count:     249
    .vgpr_spill_count: 0
    .wavefront_size: 64
